# row-group synchronisation (4 workgroups owning the same 128 rows, one counter per row tile) replaces the grid barrier after BRANCH, OUTPROJ and FFN1; BRANCH tile order remapped to the same row groupin
# baseline (speedup 1.0000x reference)
; #define LAS __attribute__((address_space(3)))
; __global__ void __launch_bounds__(256, 2) mega_kernel(Params p) {
;   __shared__ __attribute__((aligned(16))) char smem[SMEM_BYTES];
;   __shared__ uint4 xb_words;
;   cg::grid_group grid = cg::this_grid();
;   if (threadIdx.x == 0) xb_words = make_uint4(0u, 0u, 0u, 0u);
;   __syncthreads();
;   const XcdBarrier xb = xcd_barrier_post((unsigned*)(p.ws + OFF_BAR), (volatile LAS unsigned*)&xb_words);
_Z11mega_kernel6Params:
	v_writelane_b32 v255, 0, 61
	s_load_dwordx4 s[76:79], s[0:1], 0xc0
	s_load_dword s3, s[0:1], 0xd0
	s_add_u32 s22, s0, 0xc8
	s_mov_b32 s92, s2
	s_addc_u32 s23, s1, 0
	v_and_b32_e32 v172, 0x3ff, v0
	v_cmp_eq_u32_e64 s[6:7], 0, v172
	s_mov_b64 s[4:5], exec
	s_nop 0
	v_writelane_b32 v254, s6, 0
	s_nop 1
	v_writelane_b32 v254, s7, 1
	s_and_b64 s[6:7], s[4:5], s[6:7]
	s_mov_b64 exec, s[6:7]
	s_cbranch_execz .LBB1_2
	v_mov_b32_e32 v2, 0
	v_mov_b32_e32 v3, v2
	v_mov_b32_e32 v4, v2
	v_mov_b32_e32 v5, v2
	v_mov_b32_e32 v1, 0x12200
	ds_write_b128 v1, v[2:5]

; DI int TID() { int t = (int)__builtin_amdgcn_workitem_id_x(); asm volatile("" : "+v"(t)); return t; }
; DI int BID() { int b = (int)__builtin_amdgcn_workgroup_id_x(); asm volatile("" : "+s"(b)); return b; }
; DI void tile_branch(const Params& p, int l, int tile, char* smem) {
;   float* Cs = (float*)smem;
;   const int tid = TID(), lane = tid & 63, w = tid >> 6, wm = w >> 1, wn = w & 1, r32 = lane & 31, hi = lane >> 5;
;   const int mi = tile & (MTN - 1), ni = tile >> MTS; const int m0 = mi * 128, n0 = ni * 128;
; DI void run_phase(const Params& p, int ph, int l, int c, char* smem) {
;     ...
;     case PH_BRANCH: for (int t = BID(); t < MTN * 8; t += gridDim.x) tile_branch(p, l, t, smem); break;
.LBB1_258:
	s_andn2_b64 vcc, exec, s[26:27]
	s_cbranch_vccnz .LBB1_273
	v_readlane_b32 s0, v255, 30
	s_cmp_gt_i32 s0, 5
	s_mov_b64 s[20:21], -1
	s_cbranch_scc0 .LBB1_268
	s_mov_b32 s17, s92
	s_bfe_u32 s0, s17, 0x10008
	s_bfe_u32 s16, s17, 0x20006
	s_andn2_b32 s17, s17, 0x1c0
	s_lshl_b32 s0, s0, 6
	s_lshl_b32 s16, s16, 7
	s_or_b32 s17, s17, s0
	s_or_b32 s17, s17, s16
	s_cmpk_gt_i32 s17, 0x3ff
	s_cbranch_scc1 .LBB1_267
	v_readlane_b32 s20, v255, 28
	v_readlane_b32 s21, v255, 29
	s_mul_hi_i32 s0, s20, 0x1180000
	s_mul_i32 s16, s20, 0x1180000
	s_mul_i32 s24, s20, 3
	s_add_u32 s20, s18, 0x1e14c000
	s_addc_u32 s21, s19, 0
	s_add_u32 s34, s18, 0x1c14c000
	s_addc_u32 s35, s19, 0
	s_add_u32 s93, s18, s16
	s_addc_u32 s42, s19, s0
	s_add_u32 s22, s18, 0x12080000
	s_addc_u32 s23, s19, 0
	s_ashr_i32 s25, s24, 31
	s_lshl_b64 s[24:25], s[24:25], 20
	s_lshl_b32 s43, s17, 7

; DI unsigned xb_ld(unsigned* p)              { return __hip_atomic_load(p, __ATOMIC_RELAXED, __HIP_MEMORY_SCOPE_AGENT); }
; DI unsigned xb_add(unsigned* p, unsigned v) { return __hip_atomic_fetch_add(p, v, __ATOMIC_RELAXED, __HIP_MEMORY_SCOPE_AGENT); }
; #define XB_SPIN(cond, bar) do { unsigned _sp = 0; while (cond) { __builtin_amdgcn_s_sleep(1); \
;     if ((++_sp & 255u) == 0u) { if (xb_ld(&(bar)[XB_TMO])) break; if (_sp > XB_SPIN_CAP) { atomicAdd(&(bar)[XB_TMO], 1u); break; } } } } while (0)
; DI void xcd_barrier(const XcdBarrier& b) {
;   asm volatile("s_waitcnt vmcnt(0)" ::: "memory");
;   __syncthreads();
;   if (threadIdx.x == 0) {
;     unsigned* bar = b.bar;
;     __builtin_amdgcn_s_waitcnt(0);
;     unsigned nloc = b.st[0], nx = b.st[1];
;     if (nloc == 0u) { xcd_barrier_complete(bar, b.x, nloc, nx); b.st[0] = nloc; b.st[1] = nx; }
;     const unsigned old = xb_add(&bar[XB_XSUB(b.x)], 1u);
;     const unsigned gen = old / nloc;
;     if (old + 1u == (gen + 1u) * nloc) {
;       __builtin_amdgcn_fence(__ATOMIC_RELEASE, "agent");
;       asm volatile("s_waitcnt vmcnt(0)" ::: "memory");
;       const unsigned og = xb_add(&bar[XB_TOP], 1u);
;       const unsigned tg = og / nx;
;       if (og + 1u == (tg + 1u) * nx) xb_add(&bar[XB_TOPGEN], 1u);
;       else XB_SPIN(xb_ld(&bar[XB_TOPGEN]) == tg, bar);
;       __builtin_amdgcn_fence(__ATOMIC_ACQUIRE, "agent");
;       xb_add(&bar[XB_XGEN(b.x)], 1u);
;       asm volatile("s_waitcnt vmcnt(0)" ::: "memory");
;     } else {
;       XB_SPIN(xb_ld(&bar[XB_XGEN(b.x)]) == gen, bar);
;       __builtin_amdgcn_fence(__ATOMIC_ACQUIRE, "agent");
;       asm volatile("s_waitcnt vmcnt(0)" ::: "memory");
;     }
;   }
;   __syncthreads();
.LBB1_428:
	s_cmp_lt_i32 s6, 2
	s_cbranch_scc1 .Lgs_global
	s_add_i32 s2, s6, 15
	s_and_b32 s0, s2, 0xff
	s_mulk_i32 s0, 0xf1
	s_lshr_b32 s0, s0, 12
	s_mul_i32 s0, s0, 17
	s_sub_i32 s0, s2, s0
	s_mov_b32 s2, 0xe0e0
	s_lshr_b32 s2, s2, s0
	s_and_b32 s2, s2, 1
	s_cmp_eq_u32 s2, 0
	s_cbranch_scc1 .Lgs_global
	s_waitcnt vmcnt(0) lgkmcnt(0)
	s_barrier
	v_readfirstlane_b32 s0, v172
	s_nop 0
	s_cmp_lg_u32 s0, 0
	s_cbranch_scc1 .Lgs_wait
	v_readlane_b32 s2, v255, 61
	s_nop 0
	s_add_i32 s2, s2, 1
	s_nop 0
	v_writelane_b32 v255, s2, 61
	s_lshl_b32 s2, s2, 2
	s_and_b32 s0, s92, 63
	s_bfe_u32 s12, s92, 0x10008
	s_lshl_b32 s12, s12, 6
	s_or_b32 s0, s0, s12
	s_lshl_b32 s0, s0, 2
	s_add_u32 s14, s18, 0x1c143800
	s_addc_u32 s15, s19, 0
	s_add_u32 s14, s14, s0
	s_addc_u32 s15, s15, 0
	s_mov_b64 s[12:13], exec
	s_mov_b64 exec, 1
	v_mov_b32_e32 v0, 1
	global_atomic_add v1, v0, s[14:15]
	s_waitcnt vmcnt(0)
	s_mov_b32 s0, 0
.Lgs_spin:
	global_load_dword v0, v1, s[14:15] sc1
	s_waitcnt vmcnt(0)
	v_readfirstlane_b32 s16, v0
	s_nop 0
	s_cmp_ge_u32 s16, s2
	s_cbranch_scc1 .Lgs_done
	s_sleep 1
	s_add_i32 s0, s0, 1
	s_cmp_lt_u32 s0, 0x40000
	s_cbranch_scc1 .Lgs_spin
.Lgs_done:
	s_mov_b64 exec, s[12:13]
	s_waitcnt vmcnt(0)
	buffer_inv sc1
	s_waitcnt vmcnt(0)
.Lgs_wait:
	s_barrier
	s_mov_b64 s[12:13], exec
	s_branch .Lgs_to180
.Lgs_global:
	s_waitcnt vmcnt(0)
	s_waitcnt lgkmcnt(0)
	s_barrier
	s_mov_b64 s[12:13], exec
	v_readlane_b32 s14, v254, 0
	v_readlane_b32 s15, v254, 1
	s_and_b64 s[14:15], s[12:13], s[14:15]
	s_mov_b64 exec, s[14:15]
	s_cbranch_execnz .LBB1_429
.Lgs_to180:
	s_getpc_b64 s[98:99]
